# GQA attention tile loop: back edge rotated (next tile's scalar/address set-up + K prefetch issue moved before the tile barrier; exit path has its own barrier)
# speedup vs baseline: 1.0060x; 1.0051x over previous
; template <int DUAL, bool BOUND> ...
;     ...
; #pragma nounroll
;   for (int t = t0; t < t1; ++t) {
;     const char* cur = smem + ((t - t0) & 1) * A_STAGE;
;     const bool more = (t + 1 < t1);
;     if (more) gload_k(t + 1);
; #pragma nounroll
;     for (int hf = 0; hf < 2; ++hf) {
;       if (hf == 1) gload_v(more ? t + 1 : t);
;     ...
;     if (more) lstore(smem + ((t - t0 + 1) & 1) * A_STAGE);
;     __syncthreads();
;   }
.LBB0_340:
	s_waitcnt lgkmcnt(0)
	s_cmp_lg_u32 s30, 32
	s_cbranch_scc0 .Lgqa_last_bar
	s_mov_b32 s11, s30
	s_add_i32 s30, s11, 1
	s_cmp_eq_u32 s11, 31
	s_cselect_b64 s[2:3], -1, 0
	s_cmp_lg_u32 s11, 31
	s_cselect_b64 s[0:1], -1, 0
	s_and_b64 vcc, exec, s[2:3]
	s_cbranch_vccnz .Lgqa_rot_334
	s_lshl_b32 s34, s30, 14
	v_lshl_add_u64 v[68:69], v[154:155], 0, s[34:35]
	v_lshl_add_u64 v[66:67], v[156:157], 0, s[34:35]
	global_load_dwordx4 v[102:105], v[68:69], off
	global_load_dwordx4 v[106:109], v[66:67], off
.Lgqa_rot_334:
	s_bitcmp1_b32 s11, 0
	s_cselect_b32 s8, 0xac00, 0
	s_add_i32 s8, s8, 0
	v_add_u32_e32 v161, s8, v0
	s_lshl_b32 s8, s30, 7
	s_and_b64 s[2:3], exec, s[2:3]
	s_cselect_b32 s2, 0xf80, s8
	s_lshl_b32 s34, s2, 1
	s_mov_b32 s31, 0
	v_add_u32_e32 v210, v161, v208
	v_lshl_add_u64 v[164:165], v[162:163], 0, s[34:35]
	v_lshl_add_u64 v[168:169], v[152:153], 0, s[34:35]
	s_mov_b64 s[8:9], -1
	s_mov_b64 s[28:29], 0
	s_barrier
	s_branch .LBB0_336
.Lgqa_last_bar:
	s_barrier
